# remaining six island barriers as single-counter arrive+poll (no return atomic, per-barrier counter word)
# speedup vs baseline: 1.0035x; 1.0035x over previous
.LBB0_545:
	v_mbcnt_lo_u32_b32 v0, -1, 0
	v_mbcnt_hi_u32_b32 v0, -1, v0
	s_waitcnt vmcnt(0)
	s_waitcnt vmcnt(0)
	v_or_b32_e32 v0, s89, v0
	v_cmp_eq_u32_e32 vcc, 0, v0
	s_barrier
	s_and_saveexec_b64 s[0:1], vcc
	s_xor_b64 s[0:1], exec, s[0:1]
	s_cbranch_execz .LBB0_598
	s_add_i32 s2, 0, 0x22028
	v_mov_b32_e32 v0, s2
	s_waitcnt vmcnt(0) expcnt(0) lgkmcnt(0)
	ds_read_b32 v2, v0
	s_add_i32 s2, 0, 0x2202c
	v_mov_b32_e32 v0, s2
	ds_read_b32 v0, v0
	s_waitcnt lgkmcnt(0)
	v_readfirstlane_b32 s2, v2
	v_readfirstlane_b32 s3, v0
	s_xor_b32 s2, s2, 32
	s_xor_b32 s3, s3, 1
	s_or_b32 s2, s2, s3
	s_cmp_lg_u32 s2, 0
	s_cbranch_scc1 .Lcb0_full
	v_readlane_b32 s2, v254, 8
	v_readlane_b32 s3, v254, 9
	v_readlane_b32 s4, v254, 20
	v_mov_b32_e32 v16, 0
	v_mov_b32_e32 v17, 1
	s_and_b32 s4, s4, 7
	s_lshl_b32 s4, s4, 8
	s_add_u32 s2, s2, s4
	s_addc_u32 s3, s3, 0
	global_atomic_add v16, v17, s[2:3] offset:2052
.Lcb0_poll:
	global_load_dword v15, v16, s[2:3] offset:2052 sc1
	s_waitcnt vmcnt(0)
	v_readfirstlane_b32 s4, v15
	s_cmp_lt_u32 s4, 32
	s_cbranch_scc1 .Lcb0_poll
	buffer_inv sc1
	s_waitcnt vmcnt(0)
	s_branch .LBB0_598
.Lcb0_full:
	s_waitcnt lgkmcnt(1)
	v_cmp_ne_u32_e32 vcc, 0, v2
	s_cbranch_vccnz .LBB0_561
	s_add_u32 s2, s66, 0x1000
	s_addc_u32 s3, s67, 0
	s_add_u32 s4, s66, 0x1100
	s_addc_u32 s5, s67, 0
	s_add_u32 s6, s66, 0x1200
	s_addc_u32 s7, s67, 0
	s_add_u32 s8, s66, 0x1300
	s_addc_u32 s9, s67, 0
	s_mov_b32 s10, 1
	v_mov_b32_e32 v16, 0
	s_branch .LBB0_549
.LBB0_548:
	s_and_b64 vcc, exec, s[26:27]
	s_cbranch_vccnz .LBB0_556

.LBB0_642:
	v_mbcnt_lo_u32_b32 v0, -1, 0
	v_mbcnt_hi_u32_b32 v0, -1, v0
	s_waitcnt vmcnt(0)
	s_waitcnt lgkmcnt(0)
	v_or_b32_e32 v0, s89, v0
	v_cmp_eq_u32_e32 vcc, 0, v0
	s_barrier
	s_and_saveexec_b64 s[0:1], vcc
	s_xor_b64 s[0:1], exec, s[0:1]
	s_cbranch_execz .LBB0_695
	s_add_i32 s2, 0, 0x22028
	v_mov_b32_e32 v0, s2
	s_waitcnt vmcnt(0) expcnt(0) lgkmcnt(0)
	ds_read_b32 v2, v0
	s_add_i32 s2, 0, 0x2202c
	v_mov_b32_e32 v0, s2
	ds_read_b32 v0, v0
	s_waitcnt lgkmcnt(0)
	v_readfirstlane_b32 s2, v2
	v_readfirstlane_b32 s3, v0
	s_xor_b32 s2, s2, 32
	s_xor_b32 s3, s3, 1
	s_or_b32 s2, s2, s3
	s_cmp_lg_u32 s2, 0
	s_cbranch_scc1 .Lcb1_full
	v_readlane_b32 s2, v254, 8
	v_readlane_b32 s3, v254, 9
	v_readlane_b32 s4, v254, 20
	v_mov_b32_e32 v16, 0
	v_mov_b32_e32 v17, 1
	s_and_b32 s4, s4, 7
	s_lshl_b32 s4, s4, 8
	s_add_u32 s2, s2, s4
	s_addc_u32 s3, s3, 0
	global_atomic_add v16, v17, s[2:3] offset:2056
.Lcb1_poll:
	global_load_dword v15, v16, s[2:3] offset:2056 sc1
	s_waitcnt vmcnt(0)
	v_readfirstlane_b32 s4, v15
	s_cmp_lt_u32 s4, 32
	s_cbranch_scc1 .Lcb1_poll
	buffer_inv sc1
	s_waitcnt vmcnt(0)
	s_branch .LBB0_695
.Lcb1_full:
	s_waitcnt lgkmcnt(1)
	v_cmp_ne_u32_e32 vcc, 0, v2
	s_cbranch_vccnz .LBB0_658
	s_add_u32 s2, s66, 0x1000
	s_addc_u32 s3, s67, 0
	s_add_u32 s4, s66, 0x1100
	s_addc_u32 s5, s67, 0
	s_add_u32 s6, s66, 0x1200
	s_addc_u32 s7, s67, 0
	s_add_u32 s8, s66, 0x1300
	s_addc_u32 s9, s67, 0
	s_mov_b32 s10, 1
	v_mov_b32_e32 v16, 0
	s_branch .LBB0_646
.LBB0_645:
	s_and_b64 vcc, exec, s[24:25]
	s_cbranch_vccnz .LBB0_653

.LBB0_790:
	v_mbcnt_lo_u32_b32 v0, -1, 0
	v_mbcnt_hi_u32_b32 v0, -1, v0
	s_waitcnt vmcnt(0)
	s_waitcnt lgkmcnt(0)
	v_or_b32_e32 v0, s89, v0
	v_cmp_eq_u32_e32 vcc, 0, v0
	s_barrier
	s_and_saveexec_b64 s[0:1], vcc
	s_xor_b64 s[0:1], exec, s[0:1]
	s_cbranch_execz .LBB0_843
	s_add_i32 s2, 0, 0x22028
	v_mov_b32_e32 v0, s2
	s_waitcnt vmcnt(0) expcnt(0) lgkmcnt(0)
	ds_read_b32 v2, v0
	s_add_i32 s2, 0, 0x2202c
	v_mov_b32_e32 v0, s2
	ds_read_b32 v0, v0
	s_waitcnt lgkmcnt(0)
	v_readfirstlane_b32 s2, v2
	v_readfirstlane_b32 s3, v0
	s_xor_b32 s2, s2, 32
	s_xor_b32 s3, s3, 1
	s_or_b32 s2, s2, s3
	s_cmp_lg_u32 s2, 0
	s_cbranch_scc1 .Lcb2_full
	v_readlane_b32 s2, v254, 8
	v_readlane_b32 s3, v254, 9
	v_readlane_b32 s4, v254, 20
	v_mov_b32_e32 v16, 0
	v_mov_b32_e32 v17, 1
	s_and_b32 s4, s4, 7
	s_lshl_b32 s4, s4, 8
	s_add_u32 s2, s2, s4
	s_addc_u32 s3, s3, 0
	global_atomic_add v16, v17, s[2:3] offset:2060
.Lcb2_poll:
	global_load_dword v15, v16, s[2:3] offset:2060 sc1
	s_waitcnt vmcnt(0)
	v_readfirstlane_b32 s4, v15
	s_cmp_lt_u32 s4, 32
	s_cbranch_scc1 .Lcb2_poll
	buffer_inv sc1
	s_waitcnt vmcnt(0)
	s_branch .LBB0_843

.LBB0_1084:
	v_mbcnt_lo_u32_b32 v0, -1, 0
	v_mbcnt_hi_u32_b32 v0, -1, v0
	s_waitcnt vmcnt(0)
	s_waitcnt lgkmcnt(0)
	v_or_b32_e32 v0, s89, v0
	v_cmp_eq_u32_e32 vcc, 0, v0
	s_barrier
	s_mov_b64 s[0:1], exec
	v_readlane_b32 s52, v254, 0
	v_readlane_b32 s60, v254, 23
	v_readlane_b32 s62, v254, 16
	v_readlane_b32 s66, v254, 28
	v_readlane_b32 s68, v254, 34
	v_readlane_b32 s70, v254, 60
	v_readlane_b32 s72, v255, 12
	v_readlane_b32 s74, v255, 10
	v_readlane_b32 s80, v254, 36
	s_and_b64 s[2:3], s[0:1], vcc
	v_readlane_b32 s56, v254, 4
	v_readlane_b32 s57, v254, 5
	v_readlane_b32 s58, v254, 6
	v_readlane_b32 s59, v254, 7
	v_readlane_b32 s61, v254, 24
	v_readlane_b32 s63, v254, 17
	v_readlane_b32 s64, v254, 26
	v_readlane_b32 s67, v254, 29
	v_readlane_b32 s69, v254, 35
	v_readlane_b32 s71, v254, 61
	v_readlane_b32 s65, v255, 14
	v_readlane_b32 s73, v255, 13
	v_readlane_b32 s75, v255, 11
	v_readlane_b32 s76, v254, 62
	v_readlane_b32 s77, v254, 63
	v_readlane_b32 s78, v255, 0
	v_readlane_b32 s81, v254, 37
	v_readlane_b32 s53, v254, 1
	v_readlane_b32 s54, v254, 2
	v_readlane_b32 s55, v254, 3
	s_mov_b64 exec, s[2:3]
	s_cbranch_execz .LBB0_1136
	s_add_i32 s2, 0, 0x22028
	v_mov_b32_e32 v0, s2
	s_waitcnt vmcnt(0) expcnt(0) lgkmcnt(0)
	ds_read_b32 v2, v0
	s_add_i32 s2, 0, 0x2202c
	v_mov_b32_e32 v0, s2
	ds_read_b32 v0, v0
	s_waitcnt lgkmcnt(0)
	v_readfirstlane_b32 s2, v2
	v_readfirstlane_b32 s3, v0
	s_xor_b32 s2, s2, 32
	s_xor_b32 s3, s3, 1
	s_or_b32 s2, s2, s3
	s_cmp_lg_u32 s2, 0
	s_cbranch_scc1 .Lcb3_full
	v_readlane_b32 s2, v254, 8
	v_readlane_b32 s3, v254, 9
	v_readlane_b32 s4, v254, 20
	v_mov_b32_e32 v16, 0
	v_mov_b32_e32 v17, 1
	s_and_b32 s4, s4, 7
	s_lshl_b32 s4, s4, 8
	s_add_u32 s2, s2, s4
	s_addc_u32 s3, s3, 0
	global_atomic_add v16, v17, s[2:3] offset:2064
.Lcb3_poll:
	global_load_dword v15, v16, s[2:3] offset:2064 sc1
	s_waitcnt vmcnt(0)
	v_readfirstlane_b32 s4, v15
	s_cmp_lt_u32 s4, 32
	s_cbranch_scc1 .Lcb3_poll
	buffer_inv sc1
	s_waitcnt vmcnt(0)
	s_branch .LBB0_1136
.Lcb3_full:
	s_waitcnt lgkmcnt(1)
	v_cmp_ne_u32_e32 vcc, 0, v2
	s_cbranch_vccnz .LBB0_1100
	s_add_u32 s2, s62, 0x1000
	s_addc_u32 s3, s63, 0
	s_add_u32 s4, s62, 0x1100
	s_addc_u32 s5, s63, 0
	s_add_u32 s6, s62, 0x1200
	s_addc_u32 s7, s63, 0
	s_add_u32 s8, s62, 0x1300
	s_addc_u32 s9, s63, 0
	s_mov_b32 s16, 1
	v_mov_b32_e32 v16, 0
	s_branch .LBB0_1088

.LBB0_1182:
	v_mbcnt_lo_u32_b32 v0, -1, 0
	v_mbcnt_hi_u32_b32 v0, -1, v0
	s_waitcnt vmcnt(0)
	s_waitcnt lgkmcnt(0)
	v_or_b32_e32 v0, s89, v0
	v_cmp_eq_u32_e32 vcc, 0, v0
	s_barrier
	s_and_saveexec_b64 s[2:3], vcc
	s_cbranch_execz .LBB0_1234
	s_add_i32 s4, 0, 0x22028
	v_mov_b32_e32 v0, s4
	s_waitcnt vmcnt(0) expcnt(0) lgkmcnt(0)
	ds_read_b32 v2, v0
	s_add_i32 s4, 0, 0x2202c
	v_mov_b32_e32 v0, s4
	ds_read_b32 v0, v0
	s_waitcnt lgkmcnt(0)
	v_readfirstlane_b32 s4, v2
	v_readfirstlane_b32 s5, v0
	s_xor_b32 s4, s4, 32
	s_xor_b32 s5, s5, 1
	s_or_b32 s4, s4, s5
	s_cmp_lg_u32 s4, 0
	s_cbranch_scc1 .Lcb4_full
	v_readlane_b32 s4, v254, 8
	v_readlane_b32 s5, v254, 9
	v_readlane_b32 s6, v254, 20
	v_mov_b32_e32 v16, 0
	v_mov_b32_e32 v17, 1
	s_and_b32 s6, s6, 7
	s_lshl_b32 s6, s6, 8
	s_add_u32 s4, s4, s6
	s_addc_u32 s5, s5, 0
	global_atomic_add v16, v17, s[4:5] offset:2068
.Lcb4_poll:
	global_load_dword v15, v16, s[4:5] offset:2068 sc1
	s_waitcnt vmcnt(0)
	v_readfirstlane_b32 s6, v15
	s_cmp_lt_u32 s6, 32
	s_cbranch_scc1 .Lcb4_poll
	buffer_inv sc1
	s_waitcnt vmcnt(0)
	s_branch .LBB0_1234
.Lcb4_full:
	s_waitcnt lgkmcnt(1)
	v_cmp_ne_u32_e32 vcc, 0, v2
	s_cbranch_vccnz .LBB0_1198
	s_add_u32 s4, s62, 0x1000
	s_addc_u32 s5, s63, 0
	s_add_u32 s6, s62, 0x1100
	s_addc_u32 s7, s63, 0
	s_add_u32 s8, s62, 0x1200
	s_addc_u32 s9, s63, 0
	s_add_u32 s10, s62, 0x1300
	s_addc_u32 s11, s63, 0
	s_mov_b32 s18, 1
	v_mov_b32_e32 v16, 0
	s_branch .LBB0_1186

.LBB0_1250:
	v_mbcnt_lo_u32_b32 v0, -1, 0
	v_mbcnt_hi_u32_b32 v0, -1, v0
	s_waitcnt vmcnt(0)
	s_nop 0
	v_or_b32_e32 v0, s89, v0
	v_cmp_eq_u32_e32 vcc, 0, v0
	s_barrier
	s_and_saveexec_b64 s[0:1], vcc
	s_cbranch_execz .LBB0_1302
	s_add_i32 s2, 0, 0x22028
	v_mov_b32_e32 v0, s2
	s_waitcnt vmcnt(0) expcnt(0) lgkmcnt(0)
	ds_read_b32 v2, v0
	s_add_i32 s2, 0, 0x2202c
	v_mov_b32_e32 v0, s2
	ds_read_b32 v0, v0
	s_waitcnt lgkmcnt(0)
	v_readfirstlane_b32 s2, v2
	v_readfirstlane_b32 s3, v0
	s_xor_b32 s2, s2, 32
	s_xor_b32 s3, s3, 1
	s_or_b32 s2, s2, s3
	s_cmp_lg_u32 s2, 0
	s_cbranch_scc1 .Lcb5_full
	v_readlane_b32 s2, v254, 8
	v_readlane_b32 s3, v254, 9
	v_readlane_b32 s4, v254, 20
	v_mov_b32_e32 v16, 0
	v_mov_b32_e32 v17, 1
	s_and_b32 s4, s4, 7
	s_lshl_b32 s4, s4, 8
	s_add_u32 s2, s2, s4
	s_addc_u32 s3, s3, 0
	global_atomic_add v16, v17, s[2:3] offset:2072
.Lcb5_poll:
	global_load_dword v15, v16, s[2:3] offset:2072 sc1
	s_waitcnt vmcnt(0)
	v_readfirstlane_b32 s4, v15
	s_cmp_lt_u32 s4, 32
	s_cbranch_scc1 .Lcb5_poll
	buffer_inv sc1
	s_waitcnt vmcnt(0)
	s_branch .LBB0_1302
